# grid barriers: the acquire invalidate (buffer_inv sc1) is issued before the release spin (waiters) / right after the top-level arrival (XCD leaders) so its ~1.7 us latency overlaps the wait; safe beca
# speedup vs baseline: 1.0067x; 1.0039x over previous
; __device__ __forceinline__ unsigned xb_ld(unsigned* p)              { return __hip_atomic_load(p, __ATOMIC_RELAXED, __HIP_MEMORY_SCOPE_AGENT); }
; __device__ __forceinline__ unsigned xb_add(unsigned* p, unsigned v) { return __hip_atomic_fetch_add(p, v, __ATOMIC_RELAXED, __HIP_MEMORY_SCOPE_AGENT); }
; #define XB_SPIN(cond, bar) do { unsigned _sp = 0; while (cond) { __builtin_amdgcn_s_sleep(1); \
;     if ((++_sp & 255u) == 0u) { if (xb_ld(&(bar)[XB_TMO])) break; if (_sp > XB_SPIN_CAP) { atomicAdd(&(bar)[XB_TMO], 1u); break; } } } } while (0)
; __device__ __forceinline__ void xcd_barrier(const XcdBarrier& b) {
;     asm volatile("s_waitcnt vmcnt(0)" ::: "memory");
;     __syncthreads();
;     if (threadIdx.x == 0) {
;         unsigned* bar = b.bar;
;         __builtin_amdgcn_s_waitcnt(0);
;         unsigned nloc = b.st[0], nx = b.st[1];
;         if (nloc == 0u) { xcd_barrier_complete(bar, b.x, nloc, nx); b.st[0] = nloc; b.st[1] = nx; }
;         const unsigned old = xb_add(&bar[XB_XSUB(b.x)], 1u);
;         const unsigned gen = old / nloc;
;         if (old + 1u == (gen + 1u) * nloc) {
;             __builtin_amdgcn_fence(__ATOMIC_RELEASE, "agent");
;             asm volatile("s_waitcnt vmcnt(0)" ::: "memory");
;             const unsigned og = xb_add(&bar[XB_TOP], 1u);
;             const unsigned tg = og / nx;
;             if (og + 1u == (tg + 1u) * nx) xb_add(&bar[XB_TOPGEN], 1u);
;             else XB_SPIN(xb_ld(&bar[XB_TOPGEN]) == tg, bar);
;             __builtin_amdgcn_fence(__ATOMIC_ACQUIRE, "agent");
;             xb_add(&bar[XB_XGEN(b.x)], 1u);
;             asm volatile("s_waitcnt vmcnt(0)" ::: "memory");
;         } else {
;             XB_SPIN(xb_ld(&bar[XB_XGEN(b.x)]) == gen, bar);
.LBB0_433:
	s_or_b64 exec, exec, s[6:7]
	v_cvt_f32_u32_e32 v4, v2
	s_waitcnt vmcnt(0)
	v_readfirstlane_b32 s6, v3
	v_sub_u32_e32 v3, 0, v2
	v_rcp_iflag_f32_e32 v4, v4
	v_add_u32_e32 v5, s6, v1
	v_mul_f32_e32 v4, 0x4f7ffffe, v4
	v_cvt_u32_f32_e32 v4, v4
	v_mul_lo_u32 v1, v3, v4
	v_mul_hi_u32 v1, v4, v1
	v_add_u32_e32 v1, v4, v1
	v_mul_hi_u32 v1, v5, v1
	v_mul_lo_u32 v3, v1, v2
	v_sub_u32_e32 v3, v5, v3
	v_add_u32_e32 v4, 1, v1
	v_cmp_ge_u32_e32 vcc, v3, v2
	s_nop 1
	v_cndmask_b32_e32 v1, v1, v4, vcc
	v_sub_u32_e32 v4, v3, v2
	v_cndmask_b32_e32 v3, v3, v4, vcc
	v_add_u32_e32 v4, 1, v1
	v_cmp_ge_u32_e32 vcc, v3, v2
	v_add_u32_e32 v3, 1, v5
	s_nop 0
	v_cndmask_b32_e32 v1, v1, v4, vcc
	v_mul_lo_u32 v4, v2, v1
	v_add_u32_e32 v2, v4, v2
	v_cmp_ne_u32_e32 vcc, v3, v2
	s_and_saveexec_b64 s[6:7], vcc
	s_xor_b64 s[6:7], exec, s[6:7]
	s_cbranch_execz .LBB0_447
	s_waitcnt lgkmcnt(0)
	v_mov_b32_e32 v0, 0
	buffer_inv sc1
	global_load_dword v2, v0, s[94:95] sc1
	s_waitcnt vmcnt(0)
	v_cmp_eq_u32_e32 vcc, v2, v1
	s_and_saveexec_b64 s[8:9], vcc
	s_cbranch_execz .LBB0_446
	s_mov_b32 s16, 1
	s_mov_b64 s[10:11], 0
	s_branch .LBB0_437

; __device__ __forceinline__ unsigned xb_ld(unsigned* p)              { return __hip_atomic_load(p, __ATOMIC_RELAXED, __HIP_MEMORY_SCOPE_AGENT); }
; #define XB_SPIN(cond, bar) do { unsigned _sp = 0; while (cond) { __builtin_amdgcn_s_sleep(1); \
;     if ((++_sp & 255u) == 0u) { if (xb_ld(&(bar)[XB_TMO])) break; if (_sp > XB_SPIN_CAP) { atomicAdd(&(bar)[XB_TMO], 1u); break; } } } } while (0)
; __device__ __forceinline__ void xcd_barrier(const XcdBarrier& b) {
;     ...
;             XB_SPIN(xb_ld(&bar[XB_XGEN(b.x)]) == gen, bar);
;             __builtin_amdgcn_fence(__ATOMIC_ACQUIRE, "agent");
;             asm volatile("s_waitcnt vmcnt(0)" ::: "memory");
.LBB0_446:
	s_or_b64 exec, exec, s[8:9]
	s_waitcnt vmcnt(0)
	s_waitcnt vmcnt(0)

; __device__ __forceinline__ unsigned xb_ld(unsigned* p)              { return __hip_atomic_load(p, __ATOMIC_RELAXED, __HIP_MEMORY_SCOPE_AGENT); }
; __device__ __forceinline__ unsigned xb_add(unsigned* p, unsigned v) { return __hip_atomic_fetch_add(p, v, __ATOMIC_RELAXED, __HIP_MEMORY_SCOPE_AGENT); }
; #define XB_SPIN(cond, bar) do { unsigned _sp = 0; while (cond) { __builtin_amdgcn_s_sleep(1); \
;     if ((++_sp & 255u) == 0u) { if (xb_ld(&(bar)[XB_TMO])) break; if (_sp > XB_SPIN_CAP) { atomicAdd(&(bar)[XB_TMO], 1u); break; } } } } while (0)
; __device__ __forceinline__ void xcd_barrier(const XcdBarrier& b) {
;     ...
;         const unsigned old = xb_add(&bar[XB_XSUB(b.x)], 1u);
;         const unsigned gen = old / nloc;
;         if (old + 1u == (gen + 1u) * nloc) {
;             __builtin_amdgcn_fence(__ATOMIC_RELEASE, "agent");
;             asm volatile("s_waitcnt vmcnt(0)" ::: "memory");
;             const unsigned og = xb_add(&bar[XB_TOP], 1u);
;             const unsigned tg = og / nx;
;             if (og + 1u == (tg + 1u) * nx) xb_add(&bar[XB_TOPGEN], 1u);
;             else XB_SPIN(xb_ld(&bar[XB_TOPGEN]) == tg, bar);
.LBB0_450:
	s_or_b64 exec, exec, s[8:9]
	buffer_inv sc1
	s_waitcnt vmcnt(0)
	v_readfirstlane_b32 s6, v2
	v_cvt_f32_u32_e32 v2, v0
	v_sub_u32_e32 v3, 0, v0
	v_add_u32_e32 v1, s6, v1
	v_readlane_b32 s6, v240, 34
	v_rcp_iflag_f32_e32 v2, v2
	v_readlane_b32 s7, v240, 35
	s_mov_b64 s[8:9], -1
	v_mul_f32_e32 v2, 0x4f7ffffe, v2
	v_cvt_u32_f32_e32 v2, v2
	v_mul_lo_u32 v3, v3, v2
	v_mul_hi_u32 v3, v2, v3
	v_add_u32_e32 v2, v2, v3
	v_mul_hi_u32 v2, v1, v2
	v_mul_lo_u32 v3, v2, v0
	v_sub_u32_e32 v3, v1, v3
	v_cmp_ge_u32_e32 vcc, v3, v0
	v_add_u32_e32 v4, 1, v2
	v_add_u32_e32 v1, 1, v1
	v_cndmask_b32_e32 v2, v2, v4, vcc
	v_sub_u32_e32 v4, v3, v0
	v_cndmask_b32_e32 v3, v3, v4, vcc
	v_cmp_ge_u32_e32 vcc, v3, v0
	v_add_u32_e32 v3, 1, v2
	s_nop 0
	v_cndmask_b32_e32 v2, v2, v3, vcc
	v_mul_lo_u32 v3, v0, v2
	v_add_u32_e32 v0, v3, v0
	v_cmp_ne_u32_e32 vcc, v1, v0
	v_mov_b64_e32 v[0:1], s[6:7]
	s_and_saveexec_b64 s[6:7], vcc
	s_cbranch_execz .LBB0_462
	v_readlane_b32 s8, v240, 34
	v_mov_b32_e32 v0, 0
	v_readlane_b32 s9, v240, 35
	s_mov_b64 s[10:11], 0
	s_nop 3
	global_load_dword v1, v0, s[8:9] sc1
	s_waitcnt vmcnt(0)
	v_cmp_eq_u32_e32 vcc, v1, v2
	s_and_saveexec_b64 s[8:9], vcc
	s_cbranch_execz .LBB0_461
	s_mov_b32 s16, 1
	s_branch .LBB0_454

; __device__ __forceinline__ unsigned xb_ld(unsigned* p)              { return __hip_atomic_load(p, __ATOMIC_RELAXED, __HIP_MEMORY_SCOPE_AGENT); }
; __device__ __forceinline__ unsigned xb_add(unsigned* p, unsigned v) { return __hip_atomic_fetch_add(p, v, __ATOMIC_RELAXED, __HIP_MEMORY_SCOPE_AGENT); }
; #define XB_SPIN(cond, bar) do { unsigned _sp = 0; while (cond) { __builtin_amdgcn_s_sleep(1); \
;     if ((++_sp & 255u) == 0u) { if (xb_ld(&(bar)[XB_TMO])) break; if (_sp > XB_SPIN_CAP) { atomicAdd(&(bar)[XB_TMO], 1u); break; } } } } while (0)
; __device__ __forceinline__ void xcd_barrier(const XcdBarrier& b) {
;     ...
;             else XB_SPIN(xb_ld(&bar[XB_TOPGEN]) == tg, bar);
;             __builtin_amdgcn_fence(__ATOMIC_ACQUIRE, "agent");
;             xb_add(&bar[XB_XGEN(b.x)], 1u);
.LBB0_464:
	s_or_b64 exec, exec, s[6:7]
	s_mov_b64 s[6:7], exec
	v_mbcnt_lo_u32_b32 v0, s6, 0
	v_mbcnt_hi_u32_b32 v0, s7, v0
	v_cmp_eq_u32_e32 vcc, 0, v0
	s_waitcnt vmcnt(0)
	s_and_saveexec_b64 s[8:9], vcc
	s_cbranch_execz .LBB0_466
	s_bcnt1_i32_b64 s6, s[6:7]
	v_mov_b32_e32 v0, 0
	v_mov_b32_e32 v1, s6
	global_atomic_add v0, v1, s[94:95]

; __device__ __forceinline__ unsigned xb_ld(unsigned* p)              { return __hip_atomic_load(p, __ATOMIC_RELAXED, __HIP_MEMORY_SCOPE_AGENT); }
; __device__ __forceinline__ unsigned xb_add(unsigned* p, unsigned v) { return __hip_atomic_fetch_add(p, v, __ATOMIC_RELAXED, __HIP_MEMORY_SCOPE_AGENT); }
; #define XB_SPIN(cond, bar) do { unsigned _sp = 0; while (cond) { __builtin_amdgcn_s_sleep(1); \
;     if ((++_sp & 255u) == 0u) { if (xb_ld(&(bar)[XB_TMO])) break; if (_sp > XB_SPIN_CAP) { atomicAdd(&(bar)[XB_TMO], 1u); break; } } } } while (0)
; __device__ __forceinline__ void xcd_barrier(const XcdBarrier& b) {
;     ...
;         const unsigned old = xb_add(&bar[XB_XSUB(b.x)], 1u);
;         const unsigned gen = old / nloc;
;         if (old + 1u == (gen + 1u) * nloc) {
;             __builtin_amdgcn_fence(__ATOMIC_RELEASE, "agent");
;             asm volatile("s_waitcnt vmcnt(0)" ::: "memory");
;             const unsigned og = xb_add(&bar[XB_TOP], 1u);
;             const unsigned tg = og / nx;
;             if (og + 1u == (tg + 1u) * nx) xb_add(&bar[XB_TOPGEN], 1u);
;             else XB_SPIN(xb_ld(&bar[XB_TOPGEN]) == tg, bar);
;             __builtin_amdgcn_fence(__ATOMIC_ACQUIRE, "agent");
;             xb_add(&bar[XB_XGEN(b.x)], 1u);
;             asm volatile("s_waitcnt vmcnt(0)" ::: "memory");
;         } else {
;             XB_SPIN(xb_ld(&bar[XB_XGEN(b.x)]) == gen, bar);
.LBB0_607:
	s_or_b64 exec, exec, s[8:9]
	v_cvt_f32_u32_e32 v4, v2
	s_waitcnt vmcnt(0)
	v_readfirstlane_b32 s8, v3
	v_sub_u32_e32 v3, 0, v2
	v_rcp_iflag_f32_e32 v4, v4
	v_add_u32_e32 v5, s8, v1
	v_mul_f32_e32 v4, 0x4f7ffffe, v4
	v_cvt_u32_f32_e32 v4, v4
	v_mul_lo_u32 v1, v3, v4
	v_mul_hi_u32 v1, v4, v1
	v_add_u32_e32 v1, v4, v1
	v_mul_hi_u32 v1, v5, v1
	v_mul_lo_u32 v3, v1, v2
	v_sub_u32_e32 v3, v5, v3
	v_add_u32_e32 v4, 1, v1
	v_cmp_ge_u32_e32 vcc, v3, v2
	s_nop 1
	v_cndmask_b32_e32 v1, v1, v4, vcc
	v_sub_u32_e32 v4, v3, v2
	v_cndmask_b32_e32 v3, v3, v4, vcc
	v_add_u32_e32 v4, 1, v1
	v_cmp_ge_u32_e32 vcc, v3, v2
	v_add_u32_e32 v3, 1, v5
	s_nop 0
	v_cndmask_b32_e32 v1, v1, v4, vcc
	v_mul_lo_u32 v4, v2, v1
	v_add_u32_e32 v2, v4, v2
	v_cmp_ne_u32_e32 vcc, v3, v2
	s_and_saveexec_b64 s[8:9], vcc
	s_xor_b64 s[8:9], exec, s[8:9]
	s_cbranch_execz .LBB0_621
	s_waitcnt lgkmcnt(0)
	v_mov_b32_e32 v0, 0
	buffer_inv sc1
	global_load_dword v2, v0, s[94:95] sc1
	s_waitcnt vmcnt(0)
	v_cmp_eq_u32_e32 vcc, v2, v1
	s_and_saveexec_b64 s[10:11], vcc
	s_cbranch_execz .LBB0_620
	s_mov_b32 s16, 1
	s_mov_b64 s[12:13], 0
	s_branch .LBB0_611

; __device__ __forceinline__ unsigned xb_ld(unsigned* p)              { return __hip_atomic_load(p, __ATOMIC_RELAXED, __HIP_MEMORY_SCOPE_AGENT); }
; #define XB_SPIN(cond, bar) do { unsigned _sp = 0; while (cond) { __builtin_amdgcn_s_sleep(1); \
;     if ((++_sp & 255u) == 0u) { if (xb_ld(&(bar)[XB_TMO])) break; if (_sp > XB_SPIN_CAP) { atomicAdd(&(bar)[XB_TMO], 1u); break; } } } } while (0)
; __device__ __forceinline__ void xcd_barrier(const XcdBarrier& b) {
;     ...
;             XB_SPIN(xb_ld(&bar[XB_XGEN(b.x)]) == gen, bar);
;             __builtin_amdgcn_fence(__ATOMIC_ACQUIRE, "agent");
;             asm volatile("s_waitcnt vmcnt(0)" ::: "memory");
.LBB0_620:
	s_or_b64 exec, exec, s[10:11]
	s_waitcnt vmcnt(0)
	s_waitcnt vmcnt(0)

; __device__ __forceinline__ unsigned xb_ld(unsigned* p)              { return __hip_atomic_load(p, __ATOMIC_RELAXED, __HIP_MEMORY_SCOPE_AGENT); }
; __device__ __forceinline__ unsigned xb_add(unsigned* p, unsigned v) { return __hip_atomic_fetch_add(p, v, __ATOMIC_RELAXED, __HIP_MEMORY_SCOPE_AGENT); }
; #define XB_SPIN(cond, bar) do { unsigned _sp = 0; while (cond) { __builtin_amdgcn_s_sleep(1); \
;     if ((++_sp & 255u) == 0u) { if (xb_ld(&(bar)[XB_TMO])) break; if (_sp > XB_SPIN_CAP) { atomicAdd(&(bar)[XB_TMO], 1u); break; } } } } while (0)
; __device__ __forceinline__ void xcd_barrier(const XcdBarrier& b) {
;     ...
;         const unsigned old = xb_add(&bar[XB_XSUB(b.x)], 1u);
;         const unsigned gen = old / nloc;
;         if (old + 1u == (gen + 1u) * nloc) {
;             __builtin_amdgcn_fence(__ATOMIC_RELEASE, "agent");
;             asm volatile("s_waitcnt vmcnt(0)" ::: "memory");
;             const unsigned og = xb_add(&bar[XB_TOP], 1u);
;             const unsigned tg = og / nx;
;             if (og + 1u == (tg + 1u) * nx) xb_add(&bar[XB_TOPGEN], 1u);
;             else XB_SPIN(xb_ld(&bar[XB_TOPGEN]) == tg, bar);
.LBB0_624:
	s_or_b64 exec, exec, s[10:11]
	buffer_inv sc1
	s_waitcnt vmcnt(0)
	v_readfirstlane_b32 s8, v2
	v_cvt_f32_u32_e32 v2, v0
	v_sub_u32_e32 v3, 0, v0
	v_add_u32_e32 v1, s8, v1
	v_readlane_b32 s8, v240, 34
	v_rcp_iflag_f32_e32 v2, v2
	v_readlane_b32 s9, v240, 35
	s_mov_b64 s[10:11], -1
	v_mul_f32_e32 v2, 0x4f7ffffe, v2
	v_cvt_u32_f32_e32 v2, v2
	v_mul_lo_u32 v3, v3, v2
	v_mul_hi_u32 v3, v2, v3
	v_add_u32_e32 v2, v2, v3
	v_mul_hi_u32 v2, v1, v2
	v_mul_lo_u32 v3, v2, v0
	v_sub_u32_e32 v3, v1, v3
	v_cmp_ge_u32_e32 vcc, v3, v0
	v_add_u32_e32 v4, 1, v2
	v_add_u32_e32 v1, 1, v1
	v_cndmask_b32_e32 v2, v2, v4, vcc
	v_sub_u32_e32 v4, v3, v0
	v_cndmask_b32_e32 v3, v3, v4, vcc
	v_cmp_ge_u32_e32 vcc, v3, v0
	v_add_u32_e32 v3, 1, v2
	s_nop 0
	v_cndmask_b32_e32 v2, v2, v3, vcc
	v_mul_lo_u32 v3, v0, v2
	v_add_u32_e32 v0, v3, v0
	v_cmp_ne_u32_e32 vcc, v1, v0
	v_mov_b64_e32 v[0:1], s[8:9]
	s_and_saveexec_b64 s[8:9], vcc
	s_cbranch_execz .LBB0_636
	v_readlane_b32 s10, v240, 34
	v_mov_b32_e32 v0, 0
	v_readlane_b32 s11, v240, 35
	s_mov_b64 s[12:13], 0
	s_nop 3
	global_load_dword v1, v0, s[10:11] sc1
	s_waitcnt vmcnt(0)
	v_cmp_eq_u32_e32 vcc, v1, v2
	s_and_saveexec_b64 s[10:11], vcc
	s_cbranch_execz .LBB0_635
	s_mov_b32 s16, 1
	s_branch .LBB0_628

; __device__ __forceinline__ unsigned xb_ld(unsigned* p)              { return __hip_atomic_load(p, __ATOMIC_RELAXED, __HIP_MEMORY_SCOPE_AGENT); }
; __device__ __forceinline__ unsigned xb_add(unsigned* p, unsigned v) { return __hip_atomic_fetch_add(p, v, __ATOMIC_RELAXED, __HIP_MEMORY_SCOPE_AGENT); }
; #define XB_SPIN(cond, bar) do { unsigned _sp = 0; while (cond) { __builtin_amdgcn_s_sleep(1); \
;     if ((++_sp & 255u) == 0u) { if (xb_ld(&(bar)[XB_TMO])) break; if (_sp > XB_SPIN_CAP) { atomicAdd(&(bar)[XB_TMO], 1u); break; } } } } while (0)
; __device__ __forceinline__ void xcd_barrier(const XcdBarrier& b) {
;     ...
;             else XB_SPIN(xb_ld(&bar[XB_TOPGEN]) == tg, bar);
;             __builtin_amdgcn_fence(__ATOMIC_ACQUIRE, "agent");
;             xb_add(&bar[XB_XGEN(b.x)], 1u);
.LBB0_638:
	s_or_b64 exec, exec, s[8:9]
	s_mov_b64 s[8:9], exec
	v_mbcnt_lo_u32_b32 v0, s8, 0
	v_mbcnt_hi_u32_b32 v0, s9, v0
	v_cmp_eq_u32_e32 vcc, 0, v0
	s_waitcnt vmcnt(0)
	s_and_saveexec_b64 s[10:11], vcc
	s_cbranch_execz .LBB0_640
	s_bcnt1_i32_b64 s8, s[8:9]
	v_mov_b32_e32 v0, 0
	v_mov_b32_e32 v1, s8
	global_atomic_add v0, v1, s[94:95]

; __device__ __forceinline__ unsigned xb_ld(unsigned* p)              { return __hip_atomic_load(p, __ATOMIC_RELAXED, __HIP_MEMORY_SCOPE_AGENT); }
; __device__ __forceinline__ unsigned xb_add(unsigned* p, unsigned v) { return __hip_atomic_fetch_add(p, v, __ATOMIC_RELAXED, __HIP_MEMORY_SCOPE_AGENT); }
; #define XB_SPIN(cond, bar) do { unsigned _sp = 0; while (cond) { __builtin_amdgcn_s_sleep(1); \
;     if ((++_sp & 255u) == 0u) { if (xb_ld(&(bar)[XB_TMO])) break; if (_sp > XB_SPIN_CAP) { atomicAdd(&(bar)[XB_TMO], 1u); break; } } } } while (0)
; __device__ __forceinline__ void xcd_barrier(const XcdBarrier& b) {
;     ...
;         const unsigned old = xb_add(&bar[XB_XSUB(b.x)], 1u);
;         const unsigned gen = old / nloc;
;         if (old + 1u == (gen + 1u) * nloc) {
;             __builtin_amdgcn_fence(__ATOMIC_RELEASE, "agent");
;             asm volatile("s_waitcnt vmcnt(0)" ::: "memory");
;             const unsigned og = xb_add(&bar[XB_TOP], 1u);
;             const unsigned tg = og / nx;
;             if (og + 1u == (tg + 1u) * nx) xb_add(&bar[XB_TOPGEN], 1u);
;             else XB_SPIN(xb_ld(&bar[XB_TOPGEN]) == tg, bar);
;             __builtin_amdgcn_fence(__ATOMIC_ACQUIRE, "agent");
;             xb_add(&bar[XB_XGEN(b.x)], 1u);
;             asm volatile("s_waitcnt vmcnt(0)" ::: "memory");
;         } else {
;             XB_SPIN(xb_ld(&bar[XB_XGEN(b.x)]) == gen, bar);
.LBB0_735:
	s_or_b64 exec, exec, s[6:7]
	v_cvt_f32_u32_e32 v4, v2
	s_waitcnt vmcnt(0)
	v_readfirstlane_b32 s6, v3
	v_sub_u32_e32 v3, 0, v2
	v_rcp_iflag_f32_e32 v4, v4
	v_add_u32_e32 v5, s6, v1
	v_mul_f32_e32 v4, 0x4f7ffffe, v4
	v_cvt_u32_f32_e32 v4, v4
	v_mul_lo_u32 v1, v3, v4
	v_mul_hi_u32 v1, v4, v1
	v_add_u32_e32 v1, v4, v1
	v_mul_hi_u32 v1, v5, v1
	v_mul_lo_u32 v3, v1, v2
	v_sub_u32_e32 v3, v5, v3
	v_add_u32_e32 v4, 1, v1
	v_cmp_ge_u32_e32 vcc, v3, v2
	s_nop 1
	v_cndmask_b32_e32 v1, v1, v4, vcc
	v_sub_u32_e32 v4, v3, v2
	v_cndmask_b32_e32 v3, v3, v4, vcc
	v_add_u32_e32 v4, 1, v1
	v_cmp_ge_u32_e32 vcc, v3, v2
	v_add_u32_e32 v3, 1, v5
	s_nop 0
	v_cndmask_b32_e32 v1, v1, v4, vcc
	v_mul_lo_u32 v4, v2, v1
	v_add_u32_e32 v2, v4, v2
	v_cmp_ne_u32_e32 vcc, v3, v2
	s_and_saveexec_b64 s[6:7], vcc
	s_xor_b64 s[6:7], exec, s[6:7]
	s_cbranch_execz .LBB0_749
	s_waitcnt lgkmcnt(0)
	v_mov_b32_e32 v0, 0
	buffer_inv sc1
	global_load_dword v2, v0, s[94:95] sc1
	s_waitcnt vmcnt(0)
	v_cmp_eq_u32_e32 vcc, v2, v1
	s_and_saveexec_b64 s[8:9], vcc
	s_cbranch_execz .LBB0_748
	s_mov_b32 s20, 1
	s_mov_b64 s[10:11], 0
	s_branch .LBB0_739

; __device__ __forceinline__ unsigned xb_ld(unsigned* p)              { return __hip_atomic_load(p, __ATOMIC_RELAXED, __HIP_MEMORY_SCOPE_AGENT); }
; __device__ __forceinline__ unsigned xb_add(unsigned* p, unsigned v) { return __hip_atomic_fetch_add(p, v, __ATOMIC_RELAXED, __HIP_MEMORY_SCOPE_AGENT); }
; #define XB_SPIN(cond, bar) do { unsigned _sp = 0; while (cond) { __builtin_amdgcn_s_sleep(1); \
;     if ((++_sp & 255u) == 0u) { if (xb_ld(&(bar)[XB_TMO])) break; if (_sp > XB_SPIN_CAP) { atomicAdd(&(bar)[XB_TMO], 1u); break; } } } } while (0)
; __device__ __forceinline__ void xcd_barrier(const XcdBarrier& b) {
;     ...
;         const unsigned old = xb_add(&bar[XB_XSUB(b.x)], 1u);
;         const unsigned gen = old / nloc;
;         if (old + 1u == (gen + 1u) * nloc) {
;             __builtin_amdgcn_fence(__ATOMIC_RELEASE, "agent");
;             asm volatile("s_waitcnt vmcnt(0)" ::: "memory");
;             const unsigned og = xb_add(&bar[XB_TOP], 1u);
;             const unsigned tg = og / nx;
;             if (og + 1u == (tg + 1u) * nx) xb_add(&bar[XB_TOPGEN], 1u);
;             else XB_SPIN(xb_ld(&bar[XB_TOPGEN]) == tg, bar);
.LBB0_752:
	s_or_b64 exec, exec, s[8:9]
	buffer_inv sc1
	s_waitcnt vmcnt(0)
	v_readfirstlane_b32 s6, v2
	v_cvt_f32_u32_e32 v2, v0
	v_sub_u32_e32 v3, 0, v0
	v_add_u32_e32 v1, s6, v1
	v_readlane_b32 s6, v240, 34
	v_rcp_iflag_f32_e32 v2, v2
	v_readlane_b32 s7, v240, 35
	s_mov_b64 s[8:9], -1
	v_mul_f32_e32 v2, 0x4f7ffffe, v2
	v_cvt_u32_f32_e32 v2, v2
	v_mul_lo_u32 v3, v3, v2
	v_mul_hi_u32 v3, v2, v3
	v_add_u32_e32 v2, v2, v3
	v_mul_hi_u32 v2, v1, v2
	v_mul_lo_u32 v3, v2, v0
	v_sub_u32_e32 v3, v1, v3
	v_cmp_ge_u32_e32 vcc, v3, v0
	v_add_u32_e32 v4, 1, v2
	v_add_u32_e32 v1, 1, v1
	v_cndmask_b32_e32 v2, v2, v4, vcc
	v_sub_u32_e32 v4, v3, v0
	v_cndmask_b32_e32 v3, v3, v4, vcc
	v_cmp_ge_u32_e32 vcc, v3, v0
	v_add_u32_e32 v3, 1, v2
	s_nop 0
	v_cndmask_b32_e32 v2, v2, v3, vcc
	v_mul_lo_u32 v3, v0, v2
	v_add_u32_e32 v0, v3, v0
	v_cmp_ne_u32_e32 vcc, v1, v0
	v_mov_b64_e32 v[0:1], s[6:7]
	s_and_saveexec_b64 s[6:7], vcc
	s_cbranch_execz .LBB0_764
	v_readlane_b32 s8, v240, 34
	v_mov_b32_e32 v0, 0
	v_readlane_b32 s9, v240, 35
	s_mov_b64 s[10:11], 0
	s_nop 3
	global_load_dword v1, v0, s[8:9] sc1
	s_waitcnt vmcnt(0)
	v_cmp_eq_u32_e32 vcc, v1, v2
	s_and_saveexec_b64 s[8:9], vcc
	s_cbranch_execz .LBB0_763
	s_mov_b32 s20, 1
	s_branch .LBB0_756

; __device__ __forceinline__ unsigned xb_ld(unsigned* p)              { return __hip_atomic_load(p, __ATOMIC_RELAXED, __HIP_MEMORY_SCOPE_AGENT); }
; __device__ __forceinline__ unsigned xb_add(unsigned* p, unsigned v) { return __hip_atomic_fetch_add(p, v, __ATOMIC_RELAXED, __HIP_MEMORY_SCOPE_AGENT); }
; #define XB_SPIN(cond, bar) do { unsigned _sp = 0; while (cond) { __builtin_amdgcn_s_sleep(1); \
;     if ((++_sp & 255u) == 0u) { if (xb_ld(&(bar)[XB_TMO])) break; if (_sp > XB_SPIN_CAP) { atomicAdd(&(bar)[XB_TMO], 1u); break; } } } } while (0)
; __device__ __forceinline__ void xcd_barrier(const XcdBarrier& b) {
;     ...
;         const unsigned old = xb_add(&bar[XB_XSUB(b.x)], 1u);
;         const unsigned gen = old / nloc;
;         if (old + 1u == (gen + 1u) * nloc) {
;             __builtin_amdgcn_fence(__ATOMIC_RELEASE, "agent");
;             asm volatile("s_waitcnt vmcnt(0)" ::: "memory");
;             const unsigned og = xb_add(&bar[XB_TOP], 1u);
;             const unsigned tg = og / nx;
;             if (og + 1u == (tg + 1u) * nx) xb_add(&bar[XB_TOPGEN], 1u);
;             else XB_SPIN(xb_ld(&bar[XB_TOPGEN]) == tg, bar);
;             __builtin_amdgcn_fence(__ATOMIC_ACQUIRE, "agent");
;             xb_add(&bar[XB_XGEN(b.x)], 1u);
;             asm volatile("s_waitcnt vmcnt(0)" ::: "memory");
;         } else {
;             XB_SPIN(xb_ld(&bar[XB_XGEN(b.x)]) == gen, bar);
.LBB0_917:
	s_or_b64 exec, exec, s[8:9]
	v_cvt_f32_u32_e32 v4, v2
	s_waitcnt vmcnt(0)
	v_readfirstlane_b32 s8, v3
	v_sub_u32_e32 v3, 0, v2
	v_rcp_iflag_f32_e32 v4, v4
	v_add_u32_e32 v5, s8, v1
	v_mul_f32_e32 v4, 0x4f7ffffe, v4
	v_cvt_u32_f32_e32 v4, v4
	v_mul_lo_u32 v1, v3, v4
	v_mul_hi_u32 v1, v4, v1
	v_add_u32_e32 v1, v4, v1
	v_mul_hi_u32 v1, v5, v1
	v_mul_lo_u32 v3, v1, v2
	v_sub_u32_e32 v3, v5, v3
	v_add_u32_e32 v4, 1, v1
	v_cmp_ge_u32_e32 vcc, v3, v2
	s_nop 1
	v_cndmask_b32_e32 v1, v1, v4, vcc
	v_sub_u32_e32 v4, v3, v2
	v_cndmask_b32_e32 v3, v3, v4, vcc
	v_add_u32_e32 v4, 1, v1
	v_cmp_ge_u32_e32 vcc, v3, v2
	v_add_u32_e32 v3, 1, v5
	s_nop 0
	v_cndmask_b32_e32 v1, v1, v4, vcc
	v_mul_lo_u32 v4, v2, v1
	v_add_u32_e32 v2, v4, v2
	v_cmp_ne_u32_e32 vcc, v3, v2
	s_and_saveexec_b64 s[8:9], vcc
	s_xor_b64 s[8:9], exec, s[8:9]
	s_cbranch_execz .LBB0_931
	s_waitcnt lgkmcnt(0)
	v_mov_b32_e32 v0, 0
	buffer_inv sc1
	global_load_dword v2, v0, s[94:95] sc1
	s_waitcnt vmcnt(0)
	v_cmp_eq_u32_e32 vcc, v2, v1
	s_and_saveexec_b64 s[10:11], vcc
	s_cbranch_execz .LBB0_930
	s_mov_b32 s22, 1
	s_mov_b64 s[12:13], 0
	s_branch .LBB0_921

; __device__ __forceinline__ unsigned xb_ld(unsigned* p)              { return __hip_atomic_load(p, __ATOMIC_RELAXED, __HIP_MEMORY_SCOPE_AGENT); }
; __device__ __forceinline__ unsigned xb_add(unsigned* p, unsigned v) { return __hip_atomic_fetch_add(p, v, __ATOMIC_RELAXED, __HIP_MEMORY_SCOPE_AGENT); }
; #define XB_SPIN(cond, bar) do { unsigned _sp = 0; while (cond) { __builtin_amdgcn_s_sleep(1); \
;     if ((++_sp & 255u) == 0u) { if (xb_ld(&(bar)[XB_TMO])) break; if (_sp > XB_SPIN_CAP) { atomicAdd(&(bar)[XB_TMO], 1u); break; } } } } while (0)
; __device__ __forceinline__ void xcd_barrier(const XcdBarrier& b) {
;     ...
;         const unsigned old = xb_add(&bar[XB_XSUB(b.x)], 1u);
;         const unsigned gen = old / nloc;
;         if (old + 1u == (gen + 1u) * nloc) {
;             __builtin_amdgcn_fence(__ATOMIC_RELEASE, "agent");
;             asm volatile("s_waitcnt vmcnt(0)" ::: "memory");
;             const unsigned og = xb_add(&bar[XB_TOP], 1u);
;             const unsigned tg = og / nx;
;             if (og + 1u == (tg + 1u) * nx) xb_add(&bar[XB_TOPGEN], 1u);
;             else XB_SPIN(xb_ld(&bar[XB_TOPGEN]) == tg, bar);
.LBB0_934:
	s_or_b64 exec, exec, s[10:11]
	buffer_inv sc1
	s_waitcnt vmcnt(0)
	v_readfirstlane_b32 s8, v2
	v_cvt_f32_u32_e32 v2, v0
	v_sub_u32_e32 v3, 0, v0
	v_add_u32_e32 v1, s8, v1
	s_mov_b64 s[10:11], -1
	v_rcp_iflag_f32_e32 v2, v2
	s_nop 0
	v_mul_f32_e32 v2, 0x4f7ffffe, v2
	v_cvt_u32_f32_e32 v2, v2
	v_mul_lo_u32 v3, v3, v2
	v_mul_hi_u32 v3, v2, v3
	v_add_u32_e32 v2, v2, v3
	v_mul_hi_u32 v2, v1, v2
	v_mul_lo_u32 v3, v2, v0
	v_sub_u32_e32 v3, v1, v3
	v_cmp_ge_u32_e32 vcc, v3, v0
	v_add_u32_e32 v4, 1, v2
	v_add_u32_e32 v1, 1, v1
	v_cndmask_b32_e32 v2, v2, v4, vcc
	v_sub_u32_e32 v4, v3, v0
	v_cndmask_b32_e32 v3, v3, v4, vcc
	v_cmp_ge_u32_e32 vcc, v3, v0
	v_add_u32_e32 v3, 1, v2
	s_nop 0
	v_cndmask_b32_e32 v2, v2, v3, vcc
	v_mul_lo_u32 v3, v0, v2
	v_add_u32_e32 v0, v3, v0
	v_cmp_ne_u32_e32 vcc, v1, v0
	v_mov_b64_e32 v[0:1], s[24:25]
	s_and_saveexec_b64 s[8:9], vcc
	s_cbranch_execz .LBB0_946
	v_mov_b32_e32 v0, 0
	global_load_dword v1, v0, s[24:25] sc1
	s_mov_b64 s[12:13], 0
	s_waitcnt vmcnt(0)
	v_cmp_eq_u32_e32 vcc, v1, v2
	s_and_saveexec_b64 s[10:11], vcc
	s_cbranch_execz .LBB0_945
	s_mov_b32 s22, 1
	s_branch .LBB0_938

; __device__ __forceinline__ unsigned xb_ld(unsigned* p)              { return __hip_atomic_load(p, __ATOMIC_RELAXED, __HIP_MEMORY_SCOPE_AGENT); }
; __device__ __forceinline__ unsigned xb_add(unsigned* p, unsigned v) { return __hip_atomic_fetch_add(p, v, __ATOMIC_RELAXED, __HIP_MEMORY_SCOPE_AGENT); }
; #define XB_SPIN(cond, bar) do { unsigned _sp = 0; while (cond) { __builtin_amdgcn_s_sleep(1); \
;     if ((++_sp & 255u) == 0u) { if (xb_ld(&(bar)[XB_TMO])) break; if (_sp > XB_SPIN_CAP) { atomicAdd(&(bar)[XB_TMO], 1u); break; } } } } while (0)
; __device__ __forceinline__ void xcd_barrier(const XcdBarrier& b) {
;     ...
;         const unsigned old = xb_add(&bar[XB_XSUB(b.x)], 1u);
;         const unsigned gen = old / nloc;
;         if (old + 1u == (gen + 1u) * nloc) {
;             __builtin_amdgcn_fence(__ATOMIC_RELEASE, "agent");
;             asm volatile("s_waitcnt vmcnt(0)" ::: "memory");
;             const unsigned og = xb_add(&bar[XB_TOP], 1u);
;             const unsigned tg = og / nx;
;             if (og + 1u == (tg + 1u) * nx) xb_add(&bar[XB_TOPGEN], 1u);
;             else XB_SPIN(xb_ld(&bar[XB_TOPGEN]) == tg, bar);
;             __builtin_amdgcn_fence(__ATOMIC_ACQUIRE, "agent");
;             xb_add(&bar[XB_XGEN(b.x)], 1u);
;             asm volatile("s_waitcnt vmcnt(0)" ::: "memory");
;         } else {
;             XB_SPIN(xb_ld(&bar[XB_XGEN(b.x)]) == gen, bar);
.LBB0_1018:
	s_or_b64 exec, exec, s[4:5]
	v_cvt_f32_u32_e32 v4, v2
	s_waitcnt vmcnt(0)
	v_readfirstlane_b32 s4, v3
	v_sub_u32_e32 v3, 0, v2
	v_rcp_iflag_f32_e32 v4, v4
	v_add_u32_e32 v5, s4, v1
	v_mul_f32_e32 v4, 0x4f7ffffe, v4
	v_cvt_u32_f32_e32 v4, v4
	v_mul_lo_u32 v1, v3, v4
	v_mul_hi_u32 v1, v4, v1
	v_add_u32_e32 v1, v4, v1
	v_mul_hi_u32 v1, v5, v1
	v_mul_lo_u32 v3, v1, v2
	v_sub_u32_e32 v3, v5, v3
	v_add_u32_e32 v4, 1, v1
	v_cmp_ge_u32_e32 vcc, v3, v2
	s_nop 1
	v_cndmask_b32_e32 v1, v1, v4, vcc
	v_sub_u32_e32 v4, v3, v2
	v_cndmask_b32_e32 v3, v3, v4, vcc
	v_add_u32_e32 v4, 1, v1
	v_cmp_ge_u32_e32 vcc, v3, v2
	v_add_u32_e32 v3, 1, v5
	s_nop 0
	v_cndmask_b32_e32 v1, v1, v4, vcc
	v_mul_lo_u32 v4, v2, v1
	v_add_u32_e32 v2, v4, v2
	v_cmp_ne_u32_e32 vcc, v3, v2
	s_and_saveexec_b64 s[4:5], vcc
	s_xor_b64 s[4:5], exec, s[4:5]
	s_cbranch_execz .LBB0_1032
	s_waitcnt lgkmcnt(0)
	v_mov_b32_e32 v0, 0
	buffer_inv sc1
	global_load_dword v2, v0, s[94:95] sc1
	s_waitcnt vmcnt(0)
	v_cmp_eq_u32_e32 vcc, v2, v1
	s_and_saveexec_b64 s[6:7], vcc
	s_cbranch_execz .LBB0_1031
	s_mov_b32 s22, 1
	s_mov_b64 s[8:9], 0
	s_branch .LBB0_1022

; __device__ __forceinline__ unsigned xb_ld(unsigned* p)              { return __hip_atomic_load(p, __ATOMIC_RELAXED, __HIP_MEMORY_SCOPE_AGENT); }
; #define XB_SPIN(cond, bar) do { unsigned _sp = 0; while (cond) { __builtin_amdgcn_s_sleep(1); \
;     if ((++_sp & 255u) == 0u) { if (xb_ld(&(bar)[XB_TMO])) break; if (_sp > XB_SPIN_CAP) { atomicAdd(&(bar)[XB_TMO], 1u); break; } } } } while (0)
; __device__ __forceinline__ void xcd_barrier(const XcdBarrier& b) {
;     ...
;             XB_SPIN(xb_ld(&bar[XB_XGEN(b.x)]) == gen, bar);
;             __builtin_amdgcn_fence(__ATOMIC_ACQUIRE, "agent");
;             asm volatile("s_waitcnt vmcnt(0)" ::: "memory");
.LBB0_1031:
	s_or_b64 exec, exec, s[6:7]
	s_waitcnt vmcnt(0)
	s_waitcnt vmcnt(0)

; __device__ __forceinline__ unsigned xb_ld(unsigned* p)              { return __hip_atomic_load(p, __ATOMIC_RELAXED, __HIP_MEMORY_SCOPE_AGENT); }
; __device__ __forceinline__ unsigned xb_add(unsigned* p, unsigned v) { return __hip_atomic_fetch_add(p, v, __ATOMIC_RELAXED, __HIP_MEMORY_SCOPE_AGENT); }
; #define XB_SPIN(cond, bar) do { unsigned _sp = 0; while (cond) { __builtin_amdgcn_s_sleep(1); \
;     if ((++_sp & 255u) == 0u) { if (xb_ld(&(bar)[XB_TMO])) break; if (_sp > XB_SPIN_CAP) { atomicAdd(&(bar)[XB_TMO], 1u); break; } } } } while (0)
; __device__ __forceinline__ void xcd_barrier(const XcdBarrier& b) {
;     ...
;         const unsigned old = xb_add(&bar[XB_XSUB(b.x)], 1u);
;         const unsigned gen = old / nloc;
;         if (old + 1u == (gen + 1u) * nloc) {
;             __builtin_amdgcn_fence(__ATOMIC_RELEASE, "agent");
;             asm volatile("s_waitcnt vmcnt(0)" ::: "memory");
;             const unsigned og = xb_add(&bar[XB_TOP], 1u);
;             const unsigned tg = og / nx;
;             if (og + 1u == (tg + 1u) * nx) xb_add(&bar[XB_TOPGEN], 1u);
;             else XB_SPIN(xb_ld(&bar[XB_TOPGEN]) == tg, bar);
.LBB0_1035:
	s_or_b64 exec, exec, s[6:7]
	buffer_inv sc1
	s_waitcnt vmcnt(0)
	v_readfirstlane_b32 s4, v2
	v_cvt_f32_u32_e32 v2, v0
	v_sub_u32_e32 v3, 0, v0
	v_add_u32_e32 v1, s4, v1
	s_mov_b64 s[6:7], -1
	v_rcp_iflag_f32_e32 v2, v2
	s_nop 0
	v_mul_f32_e32 v2, 0x4f7ffffe, v2
	v_cvt_u32_f32_e32 v2, v2
	v_mul_lo_u32 v3, v3, v2
	v_mul_hi_u32 v3, v2, v3
	v_add_u32_e32 v2, v2, v3
	v_mul_hi_u32 v2, v1, v2
	v_mul_lo_u32 v3, v2, v0
	v_sub_u32_e32 v3, v1, v3
	v_cmp_ge_u32_e32 vcc, v3, v0
	v_add_u32_e32 v4, 1, v2
	v_add_u32_e32 v1, 1, v1
	v_cndmask_b32_e32 v2, v2, v4, vcc
	v_sub_u32_e32 v4, v3, v0
	v_cndmask_b32_e32 v3, v3, v4, vcc
	v_cmp_ge_u32_e32 vcc, v3, v0
	v_add_u32_e32 v3, 1, v2
	s_nop 0
	v_cndmask_b32_e32 v2, v2, v3, vcc
	v_mul_lo_u32 v3, v0, v2
	v_add_u32_e32 v0, v3, v0
	v_cmp_ne_u32_e32 vcc, v1, v0
	v_mov_b64_e32 v[0:1], s[24:25]
	s_and_saveexec_b64 s[4:5], vcc
	s_cbranch_execz .LBB0_1047
	v_mov_b32_e32 v0, 0
	global_load_dword v1, v0, s[24:25] sc1
	s_mov_b64 s[8:9], 0
	s_waitcnt vmcnt(0)
	v_cmp_eq_u32_e32 vcc, v1, v2
	s_and_saveexec_b64 s[6:7], vcc
	s_cbranch_execz .LBB0_1046
	s_mov_b32 s22, 1
	s_branch .LBB0_1039

; __device__ __forceinline__ unsigned xb_ld(unsigned* p)              { return __hip_atomic_load(p, __ATOMIC_RELAXED, __HIP_MEMORY_SCOPE_AGENT); }
; __device__ __forceinline__ unsigned xb_add(unsigned* p, unsigned v) { return __hip_atomic_fetch_add(p, v, __ATOMIC_RELAXED, __HIP_MEMORY_SCOPE_AGENT); }
; #define XB_SPIN(cond, bar) do { unsigned _sp = 0; while (cond) { __builtin_amdgcn_s_sleep(1); \
;     if ((++_sp & 255u) == 0u) { if (xb_ld(&(bar)[XB_TMO])) break; if (_sp > XB_SPIN_CAP) { atomicAdd(&(bar)[XB_TMO], 1u); break; } } } } while (0)
; __device__ __forceinline__ void xcd_barrier(const XcdBarrier& b) {
;     ...
;             else XB_SPIN(xb_ld(&bar[XB_TOPGEN]) == tg, bar);
;             __builtin_amdgcn_fence(__ATOMIC_ACQUIRE, "agent");
;             xb_add(&bar[XB_XGEN(b.x)], 1u);
.LBB0_1049:
	s_or_b64 exec, exec, s[4:5]
	s_mov_b64 s[4:5], exec
	v_mbcnt_lo_u32_b32 v0, s4, 0
	v_mbcnt_hi_u32_b32 v0, s5, v0
	v_cmp_eq_u32_e32 vcc, 0, v0
	s_waitcnt vmcnt(0)
	s_and_saveexec_b64 s[6:7], vcc
	s_cbranch_execz .LBB0_1051
	s_bcnt1_i32_b64 s4, s[4:5]
	v_mov_b32_e32 v0, 0
	v_mov_b32_e32 v1, s4
	global_atomic_add v0, v1, s[94:95]

; __device__ __forceinline__ unsigned xb_ld(unsigned* p)              { return __hip_atomic_load(p, __ATOMIC_RELAXED, __HIP_MEMORY_SCOPE_AGENT); }
; __device__ __forceinline__ unsigned xb_add(unsigned* p, unsigned v) { return __hip_atomic_fetch_add(p, v, __ATOMIC_RELAXED, __HIP_MEMORY_SCOPE_AGENT); }
; #define XB_SPIN(cond, bar) do { unsigned _sp = 0; while (cond) { __builtin_amdgcn_s_sleep(1); \
;     if ((++_sp & 255u) == 0u) { if (xb_ld(&(bar)[XB_TMO])) break; if (_sp > XB_SPIN_CAP) { atomicAdd(&(bar)[XB_TMO], 1u); break; } } } } while (0)
; __device__ __forceinline__ void xcd_barrier(const XcdBarrier& b) {
;     ...
;         const unsigned old = xb_add(&bar[XB_XSUB(b.x)], 1u);
;         const unsigned gen = old / nloc;
;         if (old + 1u == (gen + 1u) * nloc) {
;             __builtin_amdgcn_fence(__ATOMIC_RELEASE, "agent");
;             asm volatile("s_waitcnt vmcnt(0)" ::: "memory");
;             const unsigned og = xb_add(&bar[XB_TOP], 1u);
;             const unsigned tg = og / nx;
;             if (og + 1u == (tg + 1u) * nx) xb_add(&bar[XB_TOPGEN], 1u);
;             else XB_SPIN(xb_ld(&bar[XB_TOPGEN]) == tg, bar);
;             __builtin_amdgcn_fence(__ATOMIC_ACQUIRE, "agent");
;             xb_add(&bar[XB_XGEN(b.x)], 1u);
;             asm volatile("s_waitcnt vmcnt(0)" ::: "memory");
;         } else {
;             XB_SPIN(xb_ld(&bar[XB_XGEN(b.x)]) == gen, bar);
.LBB0_1218:
	s_or_b64 exec, exec, s[6:7]
	v_cvt_f32_u32_e32 v4, v2
	s_waitcnt vmcnt(0)
	v_readfirstlane_b32 s6, v3
	v_sub_u32_e32 v3, 0, v2
	v_rcp_iflag_f32_e32 v4, v4
	v_add_u32_e32 v5, s6, v1
	v_mul_f32_e32 v4, 0x4f7ffffe, v4
	v_cvt_u32_f32_e32 v4, v4
	v_mul_lo_u32 v1, v3, v4
	v_mul_hi_u32 v1, v4, v1
	v_add_u32_e32 v1, v4, v1
	v_mul_hi_u32 v1, v5, v1
	v_mul_lo_u32 v3, v1, v2
	v_sub_u32_e32 v3, v5, v3
	v_add_u32_e32 v4, 1, v1
	v_cmp_ge_u32_e32 vcc, v3, v2
	s_nop 1
	v_cndmask_b32_e32 v1, v1, v4, vcc
	v_sub_u32_e32 v4, v3, v2
	v_cndmask_b32_e32 v3, v3, v4, vcc
	v_add_u32_e32 v4, 1, v1
	v_cmp_ge_u32_e32 vcc, v3, v2
	v_add_u32_e32 v3, 1, v5
	s_nop 0
	v_cndmask_b32_e32 v1, v1, v4, vcc
	v_mul_lo_u32 v4, v2, v1
	v_add_u32_e32 v2, v4, v2
	v_cmp_ne_u32_e32 vcc, v3, v2
	s_and_saveexec_b64 s[6:7], vcc
	s_xor_b64 s[6:7], exec, s[6:7]
	s_cbranch_execz .LBB0_1232
	s_waitcnt lgkmcnt(0)
	v_mov_b32_e32 v0, 0
	buffer_inv sc1
	global_load_dword v2, v0, s[94:95] sc1
	s_waitcnt vmcnt(0)
	v_cmp_eq_u32_e32 vcc, v2, v1
	s_and_saveexec_b64 s[8:9], vcc
	s_cbranch_execz .LBB0_1231
	s_mov_b32 s22, 1
	s_mov_b64 s[10:11], 0
	s_branch .LBB0_1222

; __device__ __forceinline__ unsigned xb_ld(unsigned* p)              { return __hip_atomic_load(p, __ATOMIC_RELAXED, __HIP_MEMORY_SCOPE_AGENT); }
; __device__ __forceinline__ unsigned xb_add(unsigned* p, unsigned v) { return __hip_atomic_fetch_add(p, v, __ATOMIC_RELAXED, __HIP_MEMORY_SCOPE_AGENT); }
; #define XB_SPIN(cond, bar) do { unsigned _sp = 0; while (cond) { __builtin_amdgcn_s_sleep(1); \
;     if ((++_sp & 255u) == 0u) { if (xb_ld(&(bar)[XB_TMO])) break; if (_sp > XB_SPIN_CAP) { atomicAdd(&(bar)[XB_TMO], 1u); break; } } } } while (0)
; __device__ __forceinline__ void xcd_barrier(const XcdBarrier& b) {
;     ...
;         const unsigned old = xb_add(&bar[XB_XSUB(b.x)], 1u);
;         const unsigned gen = old / nloc;
;         if (old + 1u == (gen + 1u) * nloc) {
;             __builtin_amdgcn_fence(__ATOMIC_RELEASE, "agent");
;             asm volatile("s_waitcnt vmcnt(0)" ::: "memory");
;             const unsigned og = xb_add(&bar[XB_TOP], 1u);
;             const unsigned tg = og / nx;
;             if (og + 1u == (tg + 1u) * nx) xb_add(&bar[XB_TOPGEN], 1u);
;             else XB_SPIN(xb_ld(&bar[XB_TOPGEN]) == tg, bar);
.LBB0_1235:
	s_or_b64 exec, exec, s[8:9]
	buffer_inv sc1
	s_waitcnt vmcnt(0)
	v_readfirstlane_b32 s6, v2
	v_cvt_f32_u32_e32 v2, v0
	v_sub_u32_e32 v3, 0, v0
	v_add_u32_e32 v1, s6, v1
	s_mov_b64 s[8:9], -1
	v_rcp_iflag_f32_e32 v2, v2
	s_nop 0
	v_mul_f32_e32 v2, 0x4f7ffffe, v2
	v_cvt_u32_f32_e32 v2, v2
	v_mul_lo_u32 v3, v3, v2
	v_mul_hi_u32 v3, v2, v3
	v_add_u32_e32 v2, v2, v3
	v_mul_hi_u32 v2, v1, v2
	v_mul_lo_u32 v3, v2, v0
	v_sub_u32_e32 v3, v1, v3
	v_cmp_ge_u32_e32 vcc, v3, v0
	v_add_u32_e32 v4, 1, v2
	v_add_u32_e32 v1, 1, v1
	v_cndmask_b32_e32 v2, v2, v4, vcc
	v_sub_u32_e32 v4, v3, v0
	v_cndmask_b32_e32 v3, v3, v4, vcc
	v_cmp_ge_u32_e32 vcc, v3, v0
	v_add_u32_e32 v3, 1, v2
	s_nop 0
	v_cndmask_b32_e32 v2, v2, v3, vcc
	v_mul_lo_u32 v3, v0, v2
	v_add_u32_e32 v0, v3, v0
	v_cmp_ne_u32_e32 vcc, v1, v0
	v_mov_b64_e32 v[0:1], s[24:25]
	s_and_saveexec_b64 s[6:7], vcc
	s_cbranch_execz .LBB0_1247
	v_mov_b32_e32 v0, 0
	global_load_dword v1, v0, s[24:25] sc1
	s_mov_b64 s[10:11], 0
	s_waitcnt vmcnt(0)
	v_cmp_eq_u32_e32 vcc, v1, v2
	s_and_saveexec_b64 s[8:9], vcc
	s_cbranch_execz .LBB0_1246
	s_mov_b32 s22, 1
	s_branch .LBB0_1239

; __device__ __forceinline__ unsigned xb_ld(unsigned* p)              { return __hip_atomic_load(p, __ATOMIC_RELAXED, __HIP_MEMORY_SCOPE_AGENT); }
; __device__ __forceinline__ unsigned xb_add(unsigned* p, unsigned v) { return __hip_atomic_fetch_add(p, v, __ATOMIC_RELAXED, __HIP_MEMORY_SCOPE_AGENT); }
; #define XB_SPIN(cond, bar) do { unsigned _sp = 0; while (cond) { __builtin_amdgcn_s_sleep(1); \
;     if ((++_sp & 255u) == 0u) { if (xb_ld(&(bar)[XB_TMO])) break; if (_sp > XB_SPIN_CAP) { atomicAdd(&(bar)[XB_TMO], 1u); break; } } } } while (0)
; __device__ __forceinline__ void xcd_barrier(const XcdBarrier& b) {
;     ...
;         const unsigned old = xb_add(&bar[XB_XSUB(b.x)], 1u);
;         const unsigned gen = old / nloc;
;         if (old + 1u == (gen + 1u) * nloc) {
;             __builtin_amdgcn_fence(__ATOMIC_RELEASE, "agent");
;             asm volatile("s_waitcnt vmcnt(0)" ::: "memory");
;             const unsigned og = xb_add(&bar[XB_TOP], 1u);
;             const unsigned tg = og / nx;
;             if (og + 1u == (tg + 1u) * nx) xb_add(&bar[XB_TOPGEN], 1u);
;             else XB_SPIN(xb_ld(&bar[XB_TOPGEN]) == tg, bar);
;             __builtin_amdgcn_fence(__ATOMIC_ACQUIRE, "agent");
;             xb_add(&bar[XB_XGEN(b.x)], 1u);
;             asm volatile("s_waitcnt vmcnt(0)" ::: "memory");
;         } else {
;             XB_SPIN(xb_ld(&bar[XB_XGEN(b.x)]) == gen, bar);
.LBB0_1357:
	s_or_b64 exec, exec, s[2:3]
	v_cvt_f32_u32_e32 v4, v2
	s_waitcnt vmcnt(0)
	v_readfirstlane_b32 s2, v3
	v_sub_u32_e32 v3, 0, v2
	v_rcp_iflag_f32_e32 v4, v4
	v_add_u32_e32 v5, s2, v1
	v_mul_f32_e32 v4, 0x4f7ffffe, v4
	v_cvt_u32_f32_e32 v4, v4
	v_mul_lo_u32 v1, v3, v4
	v_mul_hi_u32 v1, v4, v1
	v_add_u32_e32 v1, v4, v1
	v_mul_hi_u32 v1, v5, v1
	v_mul_lo_u32 v3, v1, v2
	v_sub_u32_e32 v3, v5, v3
	v_add_u32_e32 v4, 1, v1
	v_cmp_ge_u32_e32 vcc, v3, v2
	s_nop 1
	v_cndmask_b32_e32 v1, v1, v4, vcc
	v_sub_u32_e32 v4, v3, v2
	v_cndmask_b32_e32 v3, v3, v4, vcc
	v_add_u32_e32 v4, 1, v1
	v_cmp_ge_u32_e32 vcc, v3, v2
	v_add_u32_e32 v3, 1, v5
	s_nop 0
	v_cndmask_b32_e32 v1, v1, v4, vcc
	v_mul_lo_u32 v4, v2, v1
	v_add_u32_e32 v2, v4, v2
	v_cmp_ne_u32_e32 vcc, v3, v2
	s_and_saveexec_b64 s[2:3], vcc
	s_xor_b64 s[2:3], exec, s[2:3]
	s_cbranch_execz .LBB0_1371
	s_waitcnt lgkmcnt(0)
	v_mov_b32_e32 v0, 0
	buffer_inv sc1
	global_load_dword v2, v0, s[94:95] sc1
	s_waitcnt vmcnt(0)
	v_cmp_eq_u32_e32 vcc, v2, v1
	s_and_saveexec_b64 s[4:5], vcc
	s_cbranch_execz .LBB0_1370
	s_mov_b32 s16, 1
	s_mov_b64 s[6:7], 0
	s_branch .LBB0_1361

; __device__ __forceinline__ unsigned xb_ld(unsigned* p)              { return __hip_atomic_load(p, __ATOMIC_RELAXED, __HIP_MEMORY_SCOPE_AGENT); }
; #define XB_SPIN(cond, bar) do { unsigned _sp = 0; while (cond) { __builtin_amdgcn_s_sleep(1); \
;     if ((++_sp & 255u) == 0u) { if (xb_ld(&(bar)[XB_TMO])) break; if (_sp > XB_SPIN_CAP) { atomicAdd(&(bar)[XB_TMO], 1u); break; } } } } while (0)
; __device__ __forceinline__ void xcd_barrier(const XcdBarrier& b) {
;     ...
;             XB_SPIN(xb_ld(&bar[XB_XGEN(b.x)]) == gen, bar);
;             __builtin_amdgcn_fence(__ATOMIC_ACQUIRE, "agent");
;             asm volatile("s_waitcnt vmcnt(0)" ::: "memory");
.LBB0_1370:
	s_or_b64 exec, exec, s[4:5]
	s_waitcnt vmcnt(0)
	s_waitcnt vmcnt(0)

; __device__ __forceinline__ unsigned xb_ld(unsigned* p)              { return __hip_atomic_load(p, __ATOMIC_RELAXED, __HIP_MEMORY_SCOPE_AGENT); }
; __device__ __forceinline__ unsigned xb_add(unsigned* p, unsigned v) { return __hip_atomic_fetch_add(p, v, __ATOMIC_RELAXED, __HIP_MEMORY_SCOPE_AGENT); }
; #define XB_SPIN(cond, bar) do { unsigned _sp = 0; while (cond) { __builtin_amdgcn_s_sleep(1); \
;     if ((++_sp & 255u) == 0u) { if (xb_ld(&(bar)[XB_TMO])) break; if (_sp > XB_SPIN_CAP) { atomicAdd(&(bar)[XB_TMO], 1u); break; } } } } while (0)
; __device__ __forceinline__ void xcd_barrier(const XcdBarrier& b) {
;     ...
;         const unsigned old = xb_add(&bar[XB_XSUB(b.x)], 1u);
;         const unsigned gen = old / nloc;
;         if (old + 1u == (gen + 1u) * nloc) {
;             __builtin_amdgcn_fence(__ATOMIC_RELEASE, "agent");
;             asm volatile("s_waitcnt vmcnt(0)" ::: "memory");
;             const unsigned og = xb_add(&bar[XB_TOP], 1u);
;             const unsigned tg = og / nx;
;             if (og + 1u == (tg + 1u) * nx) xb_add(&bar[XB_TOPGEN], 1u);
;             else XB_SPIN(xb_ld(&bar[XB_TOPGEN]) == tg, bar);
.LBB0_1374:
	s_or_b64 exec, exec, s[4:5]
	buffer_inv sc1
	v_cvt_f32_u32_e32 v3, v0
	s_waitcnt vmcnt(0)
	v_readfirstlane_b32 s2, v2
	s_mov_b64 s[4:5], -1
	v_rcp_iflag_f32_e32 v3, v3
	v_add_u32_e32 v1, s2, v1
	v_add_u32_e32 v4, 1, v1
	v_mul_f32_e32 v2, 0x4f7ffffe, v3
	v_cvt_u32_f32_e32 v2, v2
	v_sub_u32_e32 v3, 0, v0
	v_mul_lo_u32 v3, v3, v2
	v_mul_hi_u32 v3, v2, v3
	v_add_u32_e32 v2, v2, v3
	v_mul_hi_u32 v2, v1, v2
	v_mul_lo_u32 v3, v2, v0
	v_sub_u32_e32 v1, v1, v3
	v_add_u32_e32 v5, 1, v2
	v_cmp_ge_u32_e32 vcc, v1, v0
	v_sub_u32_e32 v3, v1, v0
	s_nop 0
	v_cndmask_b32_e32 v2, v2, v5, vcc
	v_cndmask_b32_e32 v1, v1, v3, vcc
	v_add_u32_e32 v3, 1, v2
	v_cmp_ge_u32_e32 vcc, v1, v0
	s_nop 1
	v_cndmask_b32_e32 v2, v2, v3, vcc
	v_mul_lo_u32 v1, v0, v2
	v_add_u32_e32 v0, v1, v0
	v_cmp_ne_u32_e32 vcc, v4, v0
	v_mov_b64_e32 v[0:1], s[24:25]
	s_and_saveexec_b64 s[2:3], vcc
	s_cbranch_execz .LBB0_1386
	v_mov_b32_e32 v0, 0
	global_load_dword v1, v0, s[24:25] sc1
	s_mov_b64 s[6:7], 0
	s_waitcnt vmcnt(0)
	v_cmp_eq_u32_e32 vcc, v1, v2
	s_and_saveexec_b64 s[4:5], vcc
	s_cbranch_execz .LBB0_1385
	s_mov_b32 s16, 1
	s_branch .LBB0_1378

; __device__ __forceinline__ unsigned xb_ld(unsigned* p)              { return __hip_atomic_load(p, __ATOMIC_RELAXED, __HIP_MEMORY_SCOPE_AGENT); }
; __device__ __forceinline__ unsigned xb_add(unsigned* p, unsigned v) { return __hip_atomic_fetch_add(p, v, __ATOMIC_RELAXED, __HIP_MEMORY_SCOPE_AGENT); }
; #define XB_SPIN(cond, bar) do { unsigned _sp = 0; while (cond) { __builtin_amdgcn_s_sleep(1); \
;     if ((++_sp & 255u) == 0u) { if (xb_ld(&(bar)[XB_TMO])) break; if (_sp > XB_SPIN_CAP) { atomicAdd(&(bar)[XB_TMO], 1u); break; } } } } while (0)
; __device__ __forceinline__ void xcd_barrier(const XcdBarrier& b) {
;     ...
;             else XB_SPIN(xb_ld(&bar[XB_TOPGEN]) == tg, bar);
;             __builtin_amdgcn_fence(__ATOMIC_ACQUIRE, "agent");
;             xb_add(&bar[XB_XGEN(b.x)], 1u);
.LBB0_1388:
	s_or_b64 exec, exec, s[2:3]
	s_mov_b64 s[2:3], exec
	v_mbcnt_lo_u32_b32 v0, s2, 0
	v_mbcnt_hi_u32_b32 v0, s3, v0
	v_cmp_eq_u32_e32 vcc, 0, v0
	s_waitcnt vmcnt(0)
	s_and_saveexec_b64 s[4:5], vcc
	s_cbranch_execz .LBB0_1390
	s_bcnt1_i32_b64 s2, s[2:3]
	v_mov_b32_e32 v0, 0
	v_mov_b32_e32 v1, s2
	global_atomic_add v0, v1, s[94:95]
